# SwiGLU epilogues rewritten by hand: row scales read up front, packed e+1, 32-bit store offsets (same arithmetic)
# baseline (speedup 1.0000x reference)
; __device__ __forceinline__ unsigned cvt_pk_bf16(float lo, float hi) { unsigned r; asm volatile("v_cvt_pk_bf16_f32 %0, %1, %2" : "=v"(r) : "v"(lo), "v"(hi)); return r; }
;     __device__ __forceinline__ void operator()(Acc& acc, const Unit& u, int wr, int wc, int fr, int fq) const {
;         const int row0 = u.pm * BM + wr * 64 + fr, col0 = u.pn * 128 + wc * 32 + 8 * fq;
; #pragma unroll
;         for (int ai = 0; ai < 2; ++ai)
; #pragma unroll
;             for (int m = 0; m < 4; ++m) {
;                 const int row = row0 + ai * HALF + m * 16;
;                 const float r = rs[u.idx * BM + wr * 64 + fr + ai * HALF + m * 16];
;                 const float c1 = -r * 1.4426950408889634f, r2 = r * r;
;                 f32x4 o[2];
; #pragma unroll
;                 for (int n = 0; n < 2; ++n) {
;                     const f32x4 g = acc[ai][0][m][n], up = acc[ai][1][m][n];
;                     const f32x4 t = g * c1; f32x4 e;
; #pragma unroll
;                     for (int i = 0; i < 4; ++i) e[i] = __builtin_amdgcn_exp2f(t[i]);
;                     const f32x4 d = e + 1.0f; f32x4 q;
; #pragma unroll
;                     for (int i = 0; i < 4; ++i) q[i] = __builtin_amdgcn_rcpf(d[i]);
;                     o[n] = (g * up) * (q * r2);
;                 }
;                 u32x4 w; w.x = cvt_pk_bf16(o[0][0], o[0][1]); w.y = cvt_pk_bf16(o[0][2], o[0][3]); w.z = cvt_pk_bf16(o[1][0], o[1][1]); w.w = cvt_pk_bf16(o[1][2], o[1][3]);
;                 *(u32x4*)(O + (size_t)row * DFF + col0) = w;
;             }
.LBB0_610:
	v_lshl_add_u32 v154, s45, 10, v146
	ds_read_b32 v200, v154
	ds_read_b32 v201, v154 offset:64
	ds_read_b32 v202, v154 offset:128
	ds_read_b32 v203, v154 offset:192
	ds_read_b32 v204, v154 offset:512
	ds_read_b32 v205, v154 offset:576
	ds_read_b32 v206, v154 offset:640
	ds_read_b32 v207, v154 offset:704
	v_lshl_or_b32 v156, s47, 7, v147
	v_lshl_add_u32 v151, s20, 8, v144
	v_lshlrev_b32_e32 v156, 1, v156
	v_mov_b32_e32 v198, 1.0
	v_mad_u32_u24 v155, v151, s42, v156
	s_waitcnt lgkmcnt(0)
	v_mul_f32_e32 v158, 0xbfb8aa3b, v200
	v_mul_f32_e32 v160, v200, v200
	v_pk_mul_f32 v[162:163], v[124:125], v[158:159] op_sel_hi:[1,0]
	v_pk_mul_f32 v[164:165], v[126:127], v[158:159] op_sel_hi:[1,0]
	v_pk_mul_f32 v[166:167], v[116:117], v[158:159] op_sel_hi:[1,0]
	v_pk_mul_f32 v[168:169], v[118:119], v[158:159] op_sel_hi:[1,0]
	v_exp_f32_e32 v162, v162
	v_exp_f32_e32 v163, v163
	v_pk_mul_f32 v[120:121], v[124:125], v[120:121]
	v_exp_f32_e32 v164, v164
	v_exp_f32_e32 v165, v165
	v_pk_mul_f32 v[122:123], v[126:127], v[122:123]
	v_exp_f32_e32 v166, v166
	v_exp_f32_e32 v167, v167
	v_pk_mul_f32 v[112:113], v[116:117], v[112:113]
	v_exp_f32_e32 v168, v168
	v_exp_f32_e32 v169, v169
	v_pk_mul_f32 v[114:115], v[118:119], v[114:115]
	v_pk_add_f32 v[162:163], v[162:163], v[198:199] op_sel_hi:[1,0]
	v_pk_add_f32 v[164:165], v[164:165], v[198:199] op_sel_hi:[1,0]
	v_pk_add_f32 v[166:167], v[166:167], v[198:199] op_sel_hi:[1,0]
	v_pk_add_f32 v[168:169], v[168:169], v[198:199] op_sel_hi:[1,0]
	v_rcp_f32_e32 v162, v162
	v_rcp_f32_e32 v163, v163
	v_rcp_f32_e32 v164, v164
	v_rcp_f32_e32 v165, v165
	v_rcp_f32_e32 v166, v166
	v_rcp_f32_e32 v167, v167
	v_rcp_f32_e32 v168, v168
	v_rcp_f32_e32 v169, v169
	v_pk_mul_f32 v[162:163], v[160:161], v[162:163] op_sel_hi:[0,1]
	v_pk_mul_f32 v[164:165], v[160:161], v[164:165] op_sel_hi:[0,1]
	v_pk_mul_f32 v[166:167], v[160:161], v[166:167] op_sel_hi:[0,1]
	v_pk_mul_f32 v[168:169], v[160:161], v[168:169] op_sel_hi:[0,1]
	v_pk_mul_f32 v[120:121], v[120:121], v[162:163]
	v_pk_mul_f32 v[122:123], v[122:123], v[164:165]
	v_pk_mul_f32 v[112:113], v[112:113], v[166:167]
	v_pk_mul_f32 v[114:115], v[114:115], v[168:169]
	v_cvt_pk_bf16_f32 v170, v120, v121
	v_cvt_pk_bf16_f32 v171, v122, v123
	v_cvt_pk_bf16_f32 v172, v112, v113
	v_cvt_pk_bf16_f32 v173, v114, v115
	global_store_dwordx4 v155, v[170:173], s[64:65]
	v_mul_f32_e32 v158, 0xbfb8aa3b, v201
	v_mul_f32_e32 v160, v201, v201
	v_pk_mul_f32 v[162:163], v[108:109], v[158:159] op_sel_hi:[1,0]
	v_pk_mul_f32 v[164:165], v[110:111], v[158:159] op_sel_hi:[1,0]
	v_pk_mul_f32 v[166:167], v[100:101], v[158:159] op_sel_hi:[1,0]
	v_pk_mul_f32 v[168:169], v[102:103], v[158:159] op_sel_hi:[1,0]
	v_exp_f32_e32 v162, v162
	v_exp_f32_e32 v163, v163
	v_pk_mul_f32 v[104:105], v[108:109], v[104:105]
	v_exp_f32_e32 v164, v164
	v_exp_f32_e32 v165, v165
	v_pk_mul_f32 v[106:107], v[110:111], v[106:107]
	v_exp_f32_e32 v166, v166
	v_exp_f32_e32 v167, v167
	v_pk_mul_f32 v[96:97], v[100:101], v[96:97]
	v_exp_f32_e32 v168, v168
	v_exp_f32_e32 v169, v169
	v_pk_mul_f32 v[98:99], v[102:103], v[98:99]
	v_pk_add_f32 v[162:163], v[162:163], v[198:199] op_sel_hi:[1,0]
	v_pk_add_f32 v[164:165], v[164:165], v[198:199] op_sel_hi:[1,0]
	v_pk_add_f32 v[166:167], v[166:167], v[198:199] op_sel_hi:[1,0]
	v_pk_add_f32 v[168:169], v[168:169], v[198:199] op_sel_hi:[1,0]
	v_rcp_f32_e32 v162, v162
	v_rcp_f32_e32 v163, v163
	v_rcp_f32_e32 v164, v164
	v_rcp_f32_e32 v165, v165
	v_rcp_f32_e32 v166, v166
	v_rcp_f32_e32 v167, v167
	v_rcp_f32_e32 v168, v168
	v_rcp_f32_e32 v169, v169
	v_pk_mul_f32 v[162:163], v[160:161], v[162:163] op_sel_hi:[0,1]
	v_pk_mul_f32 v[164:165], v[160:161], v[164:165] op_sel_hi:[0,1]
	v_pk_mul_f32 v[166:167], v[160:161], v[166:167] op_sel_hi:[0,1]
	v_pk_mul_f32 v[168:169], v[160:161], v[168:169] op_sel_hi:[0,1]
	v_pk_mul_f32 v[104:105], v[104:105], v[162:163]
	v_pk_mul_f32 v[106:107], v[106:107], v[164:165]
	v_pk_mul_f32 v[96:97], v[96:97], v[166:167]
	v_pk_mul_f32 v[98:99], v[98:99], v[168:169]
	v_cvt_pk_bf16_f32 v176, v104, v105
	v_cvt_pk_bf16_f32 v177, v106, v107
	v_cvt_pk_bf16_f32 v178, v96, v97
	v_cvt_pk_bf16_f32 v179, v98, v99
	v_add_u32_e32 v175, 0x16000, v155
	global_store_dwordx4 v175, v[176:179], s[64:65]
	v_mul_f32_e32 v158, 0xbfb8aa3b, v202
	v_mul_f32_e32 v160, v202, v202
	v_pk_mul_f32 v[162:163], v[92:93], v[158:159] op_sel_hi:[1,0]
	v_pk_mul_f32 v[164:165], v[94:95], v[158:159] op_sel_hi:[1,0]
	v_pk_mul_f32 v[166:167], v[84:85], v[158:159] op_sel_hi:[1,0]
	v_pk_mul_f32 v[168:169], v[86:87], v[158:159] op_sel_hi:[1,0]
	v_exp_f32_e32 v162, v162
	v_exp_f32_e32 v163, v163
	v_pk_mul_f32 v[88:89], v[92:93], v[88:89]
	v_exp_f32_e32 v164, v164
	v_exp_f32_e32 v165, v165
	v_pk_mul_f32 v[90:91], v[94:95], v[90:91]
	v_exp_f32_e32 v166, v166
	v_exp_f32_e32 v167, v167
	v_pk_mul_f32 v[80:81], v[84:85], v[80:81]
	v_exp_f32_e32 v168, v168
	v_exp_f32_e32 v169, v169
	v_pk_mul_f32 v[82:83], v[86:87], v[82:83]
	v_pk_add_f32 v[162:163], v[162:163], v[198:199] op_sel_hi:[1,0]
	v_pk_add_f32 v[164:165], v[164:165], v[198:199] op_sel_hi:[1,0]
	v_pk_add_f32 v[166:167], v[166:167], v[198:199] op_sel_hi:[1,0]
	v_pk_add_f32 v[168:169], v[168:169], v[198:199] op_sel_hi:[1,0]
	v_rcp_f32_e32 v162, v162
	v_rcp_f32_e32 v163, v163
	v_rcp_f32_e32 v164, v164
	v_rcp_f32_e32 v165, v165
	v_rcp_f32_e32 v166, v166
	v_rcp_f32_e32 v167, v167
	v_rcp_f32_e32 v168, v168
	v_rcp_f32_e32 v169, v169
	v_pk_mul_f32 v[162:163], v[160:161], v[162:163] op_sel_hi:[0,1]
	v_pk_mul_f32 v[164:165], v[160:161], v[164:165] op_sel_hi:[0,1]
	v_pk_mul_f32 v[166:167], v[160:161], v[166:167] op_sel_hi:[0,1]
	v_pk_mul_f32 v[168:169], v[160:161], v[168:169] op_sel_hi:[0,1]
; __device__ __forceinline__ unsigned cvt_pk_bf16(float lo, float hi) { unsigned r; asm volatile("v_cvt_pk_bf16_f32 %0, %1, %2" : "=v"(r) : "v"(lo), "v"(hi)); return r; }
;     __device__ __forceinline__ void operator()(Acc& acc, const Unit& u, int wr, int wc, int fr, int fq) const {
;         const int row0 = u.pm * BM + wr * 64 + fr, col0 = u.pn * 128 + wc * 32 + 8 * fq;
; #pragma unroll
;         for (int ai = 0; ai < 2; ++ai)
; #pragma unroll
;             for (int m = 0; m < 4; ++m) {
;                 const int row = row0 + ai * HALF + m * 16;
;                 const float r = rs[u.idx * BM + wr * 64 + fr + ai * HALF + m * 16];
;                 const float c1 = -r * 1.4426950408889634f, r2 = r * r;
;                 f32x4 o[2];
; #pragma unroll
;                 for (int n = 0; n < 2; ++n) {
;                     const f32x4 g = acc[ai][0][m][n], up = acc[ai][1][m][n];
;                     const f32x4 t = g * c1; f32x4 e;
; #pragma unroll
;                     for (int i = 0; i < 4; ++i) e[i] = __builtin_amdgcn_exp2f(t[i]);
;                     const f32x4 d = e + 1.0f; f32x4 q;
; #pragma unroll
;                     for (int i = 0; i < 4; ++i) q[i] = __builtin_amdgcn_rcpf(d[i]);
;                     o[n] = (g * up) * (q * r2);
;                 }
;                 u32x4 w; w.x = cvt_pk_bf16(o[0][0], o[0][1]); w.y = cvt_pk_bf16(o[0][2], o[0][3]); w.z = cvt_pk_bf16(o[1][0], o[1][1]); w.w = cvt_pk_bf16(o[1][2], o[1][3]);
;                 *(u32x4*)(O + (size_t)row * DFF + col0) = w;
;             }
	v_pk_mul_f32 v[88:89], v[88:89], v[162:163]
	v_pk_mul_f32 v[90:91], v[90:91], v[164:165]
	v_pk_mul_f32 v[80:81], v[80:81], v[166:167]
	v_pk_mul_f32 v[82:83], v[82:83], v[168:169]
	v_cvt_pk_bf16_f32 v170, v88, v89
	v_cvt_pk_bf16_f32 v171, v90, v91
	v_cvt_pk_bf16_f32 v172, v80, v81
	v_cvt_pk_bf16_f32 v173, v82, v83
	v_add_u32_e32 v174, 0x2c000, v155
	global_store_dwordx4 v174, v[170:173], s[64:65]
	v_mul_f32_e32 v158, 0xbfb8aa3b, v203
	v_mul_f32_e32 v160, v203, v203
	v_pk_mul_f32 v[162:163], v[76:77], v[158:159] op_sel_hi:[1,0]
	v_pk_mul_f32 v[164:165], v[78:79], v[158:159] op_sel_hi:[1,0]
	v_pk_mul_f32 v[166:167], v[68:69], v[158:159] op_sel_hi:[1,0]
	v_pk_mul_f32 v[168:169], v[70:71], v[158:159] op_sel_hi:[1,0]
	v_exp_f32_e32 v162, v162
	v_exp_f32_e32 v163, v163
	v_pk_mul_f32 v[72:73], v[76:77], v[72:73]
	v_exp_f32_e32 v164, v164
	v_exp_f32_e32 v165, v165
	v_pk_mul_f32 v[74:75], v[78:79], v[74:75]
	v_exp_f32_e32 v166, v166
	v_exp_f32_e32 v167, v167
	v_pk_mul_f32 v[64:65], v[68:69], v[64:65]
	v_exp_f32_e32 v168, v168
	v_exp_f32_e32 v169, v169
	v_pk_mul_f32 v[66:67], v[70:71], v[66:67]
	v_pk_add_f32 v[162:163], v[162:163], v[198:199] op_sel_hi:[1,0]
	v_pk_add_f32 v[164:165], v[164:165], v[198:199] op_sel_hi:[1,0]
	v_pk_add_f32 v[166:167], v[166:167], v[198:199] op_sel_hi:[1,0]
	v_pk_add_f32 v[168:169], v[168:169], v[198:199] op_sel_hi:[1,0]
	v_rcp_f32_e32 v162, v162
	v_rcp_f32_e32 v163, v163
	v_rcp_f32_e32 v164, v164
	v_rcp_f32_e32 v165, v165
	v_rcp_f32_e32 v166, v166
	v_rcp_f32_e32 v167, v167
	v_rcp_f32_e32 v168, v168
	v_rcp_f32_e32 v169, v169
	v_pk_mul_f32 v[162:163], v[160:161], v[162:163] op_sel_hi:[0,1]
	v_pk_mul_f32 v[164:165], v[160:161], v[164:165] op_sel_hi:[0,1]
	v_pk_mul_f32 v[166:167], v[160:161], v[166:167] op_sel_hi:[0,1]
	v_pk_mul_f32 v[168:169], v[160:161], v[168:169] op_sel_hi:[0,1]
	v_pk_mul_f32 v[72:73], v[72:73], v[162:163]
	v_pk_mul_f32 v[74:75], v[74:75], v[164:165]
	v_pk_mul_f32 v[64:65], v[64:65], v[166:167]
	v_pk_mul_f32 v[66:67], v[66:67], v[168:169]
	v_cvt_pk_bf16_f32 v176, v72, v73
	v_cvt_pk_bf16_f32 v177, v74, v75
	v_cvt_pk_bf16_f32 v178, v64, v65
	v_cvt_pk_bf16_f32 v179, v66, v67
	v_add_u32_e32 v175, 0x42000, v155
	global_store_dwordx4 v175, v[176:179], s[64:65]
	v_mul_f32_e32 v158, 0xbfb8aa3b, v204
	v_mul_f32_e32 v160, v204, v204
	v_pk_mul_f32 v[162:163], v[60:61], v[158:159] op_sel_hi:[1,0]
	v_pk_mul_f32 v[164:165], v[62:63], v[158:159] op_sel_hi:[1,0]
	v_pk_mul_f32 v[166:167], v[52:53], v[158:159] op_sel_hi:[1,0]
	v_pk_mul_f32 v[168:169], v[54:55], v[158:159] op_sel_hi:[1,0]
	v_exp_f32_e32 v162, v162
	v_exp_f32_e32 v163, v163
	v_pk_mul_f32 v[56:57], v[60:61], v[56:57]
	v_exp_f32_e32 v164, v164
	v_exp_f32_e32 v165, v165
	v_pk_mul_f32 v[58:59], v[62:63], v[58:59]
	v_exp_f32_e32 v166, v166
	v_exp_f32_e32 v167, v167
	v_pk_mul_f32 v[48:49], v[52:53], v[48:49]
	v_exp_f32_e32 v168, v168
	v_exp_f32_e32 v169, v169
	v_pk_mul_f32 v[50:51], v[54:55], v[50:51]
	v_pk_add_f32 v[162:163], v[162:163], v[198:199] op_sel_hi:[1,0]
	v_pk_add_f32 v[164:165], v[164:165], v[198:199] op_sel_hi:[1,0]
	v_pk_add_f32 v[166:167], v[166:167], v[198:199] op_sel_hi:[1,0]
	v_pk_add_f32 v[168:169], v[168:169], v[198:199] op_sel_hi:[1,0]
	v_rcp_f32_e32 v162, v162
	v_rcp_f32_e32 v163, v163
	v_rcp_f32_e32 v164, v164
	v_rcp_f32_e32 v165, v165
	v_rcp_f32_e32 v166, v166
	v_rcp_f32_e32 v167, v167
	v_rcp_f32_e32 v168, v168
	v_rcp_f32_e32 v169, v169
	v_pk_mul_f32 v[162:163], v[160:161], v[162:163] op_sel_hi:[0,1]
	v_pk_mul_f32 v[164:165], v[160:161], v[164:165] op_sel_hi:[0,1]
	v_pk_mul_f32 v[166:167], v[160:161], v[166:167] op_sel_hi:[0,1]
	v_pk_mul_f32 v[168:169], v[160:161], v[168:169] op_sel_hi:[0,1]
	v_pk_mul_f32 v[56:57], v[56:57], v[162:163]
	v_pk_mul_f32 v[58:59], v[58:59], v[164:165]
	v_pk_mul_f32 v[48:49], v[48:49], v[166:167]
	v_pk_mul_f32 v[50:51], v[50:51], v[168:169]
	v_cvt_pk_bf16_f32 v170, v56, v57
	v_cvt_pk_bf16_f32 v171, v58, v59
	v_cvt_pk_bf16_f32 v172, v48, v49
	v_cvt_pk_bf16_f32 v173, v50, v51
	v_add_u32_e32 v174, 0xb0000, v155
	global_store_dwordx4 v174, v[170:173], s[64:65]
	v_mul_f32_e32 v158, 0xbfb8aa3b, v205
	v_mul_f32_e32 v160, v205, v205
	v_pk_mul_f32 v[162:163], v[44:45], v[158:159] op_sel_hi:[1,0]
	v_pk_mul_f32 v[164:165], v[46:47], v[158:159] op_sel_hi:[1,0]
	v_pk_mul_f32 v[166:167], v[36:37], v[158:159] op_sel_hi:[1,0]
	v_pk_mul_f32 v[168:169], v[38:39], v[158:159] op_sel_hi:[1,0]
	v_exp_f32_e32 v162, v162
	v_exp_f32_e32 v163, v163
	v_pk_mul_f32 v[40:41], v[44:45], v[40:41]
	v_exp_f32_e32 v164, v164
	v_exp_f32_e32 v165, v165
	v_pk_mul_f32 v[42:43], v[46:47], v[42:43]
	v_exp_f32_e32 v166, v166
	v_exp_f32_e32 v167, v167
	v_pk_mul_f32 v[32:33], v[36:37], v[32:33]
	v_exp_f32_e32 v168, v168
	v_exp_f32_e32 v169, v169
	v_pk_mul_f32 v[34:35], v[38:39], v[34:35]
	v_pk_add_f32 v[162:163], v[162:163], v[198:199] op_sel_hi:[1,0]
; __device__ __forceinline__ unsigned cvt_pk_bf16(float lo, float hi) { unsigned r; asm volatile("v_cvt_pk_bf16_f32 %0, %1, %2" : "=v"(r) : "v"(lo), "v"(hi)); return r; }
;     __device__ __forceinline__ void operator()(Acc& acc, const Unit& u, int wr, int wc, int fr, int fq) const {
;         const int row0 = u.pm * BM + wr * 64 + fr, col0 = u.pn * 128 + wc * 32 + 8 * fq;
; #pragma unroll
;         for (int ai = 0; ai < 2; ++ai)
; #pragma unroll
;             for (int m = 0; m < 4; ++m) {
;                 const int row = row0 + ai * HALF + m * 16;
;                 const float r = rs[u.idx * BM + wr * 64 + fr + ai * HALF + m * 16];
;                 const float c1 = -r * 1.4426950408889634f, r2 = r * r;
;                 f32x4 o[2];
; #pragma unroll
;                 for (int n = 0; n < 2; ++n) {
;                     const f32x4 g = acc[ai][0][m][n], up = acc[ai][1][m][n];
;                     const f32x4 t = g * c1; f32x4 e;
; #pragma unroll
;                     for (int i = 0; i < 4; ++i) e[i] = __builtin_amdgcn_exp2f(t[i]);
;                     const f32x4 d = e + 1.0f; f32x4 q;
; #pragma unroll
;                     for (int i = 0; i < 4; ++i) q[i] = __builtin_amdgcn_rcpf(d[i]);
;                     o[n] = (g * up) * (q * r2);
;                 }
;                 u32x4 w; w.x = cvt_pk_bf16(o[0][0], o[0][1]); w.y = cvt_pk_bf16(o[0][2], o[0][3]); w.z = cvt_pk_bf16(o[1][0], o[1][1]); w.w = cvt_pk_bf16(o[1][2], o[1][3]);
;                 *(u32x4*)(O + (size_t)row * DFF + col0) = w;
;             }
	v_pk_add_f32 v[164:165], v[164:165], v[198:199] op_sel_hi:[1,0]
	v_pk_add_f32 v[166:167], v[166:167], v[198:199] op_sel_hi:[1,0]
	v_pk_add_f32 v[168:169], v[168:169], v[198:199] op_sel_hi:[1,0]
	v_rcp_f32_e32 v162, v162
	v_rcp_f32_e32 v163, v163
	v_rcp_f32_e32 v164, v164
	v_rcp_f32_e32 v165, v165
	v_rcp_f32_e32 v166, v166
	v_rcp_f32_e32 v167, v167
	v_rcp_f32_e32 v168, v168
	v_rcp_f32_e32 v169, v169
	v_pk_mul_f32 v[162:163], v[160:161], v[162:163] op_sel_hi:[0,1]
	v_pk_mul_f32 v[164:165], v[160:161], v[164:165] op_sel_hi:[0,1]
	v_pk_mul_f32 v[166:167], v[160:161], v[166:167] op_sel_hi:[0,1]
	v_pk_mul_f32 v[168:169], v[160:161], v[168:169] op_sel_hi:[0,1]
	v_pk_mul_f32 v[40:41], v[40:41], v[162:163]
	v_pk_mul_f32 v[42:43], v[42:43], v[164:165]
	v_pk_mul_f32 v[32:33], v[32:33], v[166:167]
	v_pk_mul_f32 v[34:35], v[34:35], v[168:169]
	v_cvt_pk_bf16_f32 v176, v40, v41
	v_cvt_pk_bf16_f32 v177, v42, v43
	v_cvt_pk_bf16_f32 v178, v32, v33
	v_cvt_pk_bf16_f32 v179, v34, v35
	v_add_u32_e32 v175, 0xc6000, v155
	global_store_dwordx4 v175, v[176:179], s[64:65]
	v_mul_f32_e32 v158, 0xbfb8aa3b, v206
	v_mul_f32_e32 v160, v206, v206
	v_pk_mul_f32 v[162:163], v[28:29], v[158:159] op_sel_hi:[1,0]
	v_pk_mul_f32 v[164:165], v[30:31], v[158:159] op_sel_hi:[1,0]
	v_pk_mul_f32 v[166:167], v[20:21], v[158:159] op_sel_hi:[1,0]
	v_pk_mul_f32 v[168:169], v[22:23], v[158:159] op_sel_hi:[1,0]
	v_exp_f32_e32 v162, v162
	v_exp_f32_e32 v163, v163
	v_pk_mul_f32 v[24:25], v[28:29], v[24:25]
	v_exp_f32_e32 v164, v164
	v_exp_f32_e32 v165, v165
	v_pk_mul_f32 v[26:27], v[30:31], v[26:27]
	v_exp_f32_e32 v166, v166
	v_exp_f32_e32 v167, v167
	v_pk_mul_f32 v[16:17], v[20:21], v[16:17]
	v_exp_f32_e32 v168, v168
	v_exp_f32_e32 v169, v169
	v_pk_mul_f32 v[18:19], v[22:23], v[18:19]
	v_pk_add_f32 v[162:163], v[162:163], v[198:199] op_sel_hi:[1,0]
	v_pk_add_f32 v[164:165], v[164:165], v[198:199] op_sel_hi:[1,0]
	v_pk_add_f32 v[166:167], v[166:167], v[198:199] op_sel_hi:[1,0]
	v_pk_add_f32 v[168:169], v[168:169], v[198:199] op_sel_hi:[1,0]
	v_rcp_f32_e32 v162, v162
	v_rcp_f32_e32 v163, v163
	v_rcp_f32_e32 v164, v164
	v_rcp_f32_e32 v165, v165
	v_rcp_f32_e32 v166, v166
	v_rcp_f32_e32 v167, v167
	v_rcp_f32_e32 v168, v168
	v_rcp_f32_e32 v169, v169
	v_pk_mul_f32 v[162:163], v[160:161], v[162:163] op_sel_hi:[0,1]
	v_pk_mul_f32 v[164:165], v[160:161], v[164:165] op_sel_hi:[0,1]
	v_pk_mul_f32 v[166:167], v[160:161], v[166:167] op_sel_hi:[0,1]
	v_pk_mul_f32 v[168:169], v[160:161], v[168:169] op_sel_hi:[0,1]
	v_pk_mul_f32 v[24:25], v[24:25], v[162:163]
	v_pk_mul_f32 v[26:27], v[26:27], v[164:165]
	v_pk_mul_f32 v[16:17], v[16:17], v[166:167]
	v_pk_mul_f32 v[18:19], v[18:19], v[168:169]
	v_cvt_pk_bf16_f32 v170, v24, v25
	v_cvt_pk_bf16_f32 v171, v26, v27
	v_cvt_pk_bf16_f32 v172, v16, v17
	v_cvt_pk_bf16_f32 v173, v18, v19
	v_add_u32_e32 v174, 0xdc000, v155
	global_store_dwordx4 v174, v[170:173], s[64:65]
	v_mul_f32_e32 v158, 0xbfb8aa3b, v207
	v_mul_f32_e32 v160, v207, v207
	v_pk_mul_f32 v[162:163], v[12:13], v[158:159] op_sel_hi:[1,0]
	v_pk_mul_f32 v[164:165], v[14:15], v[158:159] op_sel_hi:[1,0]
	v_pk_mul_f32 v[166:167], v[4:5], v[158:159] op_sel_hi:[1,0]
	v_pk_mul_f32 v[168:169], v[6:7], v[158:159] op_sel_hi:[1,0]
	v_exp_f32_e32 v162, v162
	v_exp_f32_e32 v163, v163
	v_pk_mul_f32 v[8:9], v[12:13], v[8:9]
	v_exp_f32_e32 v164, v164
	v_exp_f32_e32 v165, v165
	v_pk_mul_f32 v[10:11], v[14:15], v[10:11]
	v_exp_f32_e32 v166, v166
	v_exp_f32_e32 v167, v167
	v_pk_mul_f32 v[0:1], v[4:5], v[0:1]
	v_exp_f32_e32 v168, v168
	v_exp_f32_e32 v169, v169
	v_pk_mul_f32 v[2:3], v[6:7], v[2:3]
	v_pk_add_f32 v[162:163], v[162:163], v[198:199] op_sel_hi:[1,0]
	v_pk_add_f32 v[164:165], v[164:165], v[198:199] op_sel_hi:[1,0]
	v_pk_add_f32 v[166:167], v[166:167], v[198:199] op_sel_hi:[1,0]
	v_pk_add_f32 v[168:169], v[168:169], v[198:199] op_sel_hi:[1,0]
	v_rcp_f32_e32 v162, v162
	v_rcp_f32_e32 v163, v163
	v_rcp_f32_e32 v164, v164
	v_rcp_f32_e32 v165, v165
	v_rcp_f32_e32 v166, v166
	v_rcp_f32_e32 v167, v167
	v_rcp_f32_e32 v168, v168
	v_rcp_f32_e32 v169, v169
	v_pk_mul_f32 v[162:163], v[160:161], v[162:163] op_sel_hi:[0,1]
	v_pk_mul_f32 v[164:165], v[160:161], v[164:165] op_sel_hi:[0,1]
	v_pk_mul_f32 v[166:167], v[160:161], v[166:167] op_sel_hi:[0,1]
	v_pk_mul_f32 v[168:169], v[160:161], v[168:169] op_sel_hi:[0,1]
	v_pk_mul_f32 v[8:9], v[8:9], v[162:163]
	v_pk_mul_f32 v[10:11], v[10:11], v[164:165]
	v_pk_mul_f32 v[0:1], v[0:1], v[166:167]
	v_pk_mul_f32 v[2:3], v[2:3], v[168:169]
	v_cvt_pk_bf16_f32 v176, v8, v9
	v_cvt_pk_bf16_f32 v177, v10, v11
	v_cvt_pk_bf16_f32 v178, v0, v1
	v_cvt_pk_bf16_f32 v179, v2, v3
	v_add_u32_e32 v175, 0xf2000, v155
	global_store_dwordx4 v175, v[176:179], s[64:65]
	s_andn2_b64 vcc, exec, s[2:3]
	s_mov_b64 s[2:3], -1
	s_mov_b32 s101, 1
	s_cbranch_vccnz .LBB0_603
	s_andn2_b64 vcc, exec, s[6:7]
	s_cbranch_vccnz .LBB0_602
	s_barrier
	s_branch .LBB0_602

; __device__ __forceinline__ unsigned cvt_pk_bf16(float lo, float hi) { unsigned r; asm volatile("v_cvt_pk_bf16_f32 %0, %1, %2" : "=v"(r) : "v"(lo), "v"(hi)); return r; }
;     __device__ __forceinline__ void operator()(Acc& acc, const Unit& u, int wr, int wc, int fr, int fq) const {
;         const int row0 = u.pm * BM + wr * 64 + fr, col0 = u.pn * 128 + wc * 32 + 8 * fq;
; #pragma unroll
;         for (int ai = 0; ai < 2; ++ai)
; #pragma unroll
;             for (int m = 0; m < 4; ++m) {
;                 const int row = row0 + ai * HALF + m * 16;
;                 const float r = rs[u.idx * BM + wr * 64 + fr + ai * HALF + m * 16];
;                 const float c1 = -r * 1.4426950408889634f, r2 = r * r;
;                 f32x4 o[2];
; #pragma unroll
;                 for (int n = 0; n < 2; ++n) {
;                     const f32x4 g = acc[ai][0][m][n], up = acc[ai][1][m][n];
;                     const f32x4 t = g * c1; f32x4 e;
; #pragma unroll
;                     for (int i = 0; i < 4; ++i) e[i] = __builtin_amdgcn_exp2f(t[i]);
;                     const f32x4 d = e + 1.0f; f32x4 q;
; #pragma unroll
;                     for (int i = 0; i < 4; ++i) q[i] = __builtin_amdgcn_rcpf(d[i]);
;                     o[n] = (g * up) * (q * r2);
;                 }
;                 u32x4 w; w.x = cvt_pk_bf16(o[0][0], o[0][1]); w.y = cvt_pk_bf16(o[0][2], o[0][3]); w.z = cvt_pk_bf16(o[1][0], o[1][1]); w.w = cvt_pk_bf16(o[1][2], o[1][3]);
;                 *(u32x4*)(O + (size_t)row * DFF + col0) = w;
;             }
.LBB0_1616:
	v_lshl_add_u32 v154, s43, 10, v146
	ds_read_b32 v200, v154
	ds_read_b32 v201, v154 offset:64
	ds_read_b32 v202, v154 offset:128
	ds_read_b32 v203, v154 offset:192
	ds_read_b32 v204, v154 offset:512
	ds_read_b32 v205, v154 offset:576
	ds_read_b32 v206, v154 offset:640
	ds_read_b32 v207, v154 offset:704
	v_lshl_or_b32 v156, s44, 7, v147
	v_lshl_add_u32 v151, s18, 8, v144
	v_lshlrev_b32_e32 v156, 1, v156
	v_mov_b32_e32 v198, 1.0
	v_mad_u32_u24 v155, v151, s40, v156
	s_waitcnt lgkmcnt(0)
	v_mul_f32_e32 v158, 0xbfb8aa3b, v200
	v_mul_f32_e32 v160, v200, v200
	v_pk_mul_f32 v[162:163], v[124:125], v[158:159] op_sel_hi:[1,0]
	v_pk_mul_f32 v[164:165], v[126:127], v[158:159] op_sel_hi:[1,0]
	v_pk_mul_f32 v[166:167], v[116:117], v[158:159] op_sel_hi:[1,0]
	v_pk_mul_f32 v[168:169], v[118:119], v[158:159] op_sel_hi:[1,0]
	v_exp_f32_e32 v162, v162
	v_exp_f32_e32 v163, v163
	v_pk_mul_f32 v[120:121], v[124:125], v[120:121]
	v_exp_f32_e32 v164, v164
	v_exp_f32_e32 v165, v165
	v_pk_mul_f32 v[122:123], v[126:127], v[122:123]
	v_exp_f32_e32 v166, v166
	v_exp_f32_e32 v167, v167
	v_pk_mul_f32 v[112:113], v[116:117], v[112:113]
	v_exp_f32_e32 v168, v168
	v_exp_f32_e32 v169, v169
	v_pk_mul_f32 v[114:115], v[118:119], v[114:115]
	v_pk_add_f32 v[162:163], v[162:163], v[198:199] op_sel_hi:[1,0]
	v_pk_add_f32 v[164:165], v[164:165], v[198:199] op_sel_hi:[1,0]
	v_pk_add_f32 v[166:167], v[166:167], v[198:199] op_sel_hi:[1,0]
	v_pk_add_f32 v[168:169], v[168:169], v[198:199] op_sel_hi:[1,0]
	v_rcp_f32_e32 v162, v162
	v_rcp_f32_e32 v163, v163
	v_rcp_f32_e32 v164, v164
	v_rcp_f32_e32 v165, v165
	v_rcp_f32_e32 v166, v166
	v_rcp_f32_e32 v167, v167
	v_rcp_f32_e32 v168, v168
	v_rcp_f32_e32 v169, v169
	v_pk_mul_f32 v[162:163], v[160:161], v[162:163] op_sel_hi:[0,1]
	v_pk_mul_f32 v[164:165], v[160:161], v[164:165] op_sel_hi:[0,1]
	v_pk_mul_f32 v[166:167], v[160:161], v[166:167] op_sel_hi:[0,1]
	v_pk_mul_f32 v[168:169], v[160:161], v[168:169] op_sel_hi:[0,1]
	v_pk_mul_f32 v[120:121], v[120:121], v[162:163]
	v_pk_mul_f32 v[122:123], v[122:123], v[164:165]
	v_pk_mul_f32 v[112:113], v[112:113], v[166:167]
	v_pk_mul_f32 v[114:115], v[114:115], v[168:169]
	v_cvt_pk_bf16_f32 v170, v120, v121
	v_cvt_pk_bf16_f32 v171, v122, v123
	v_cvt_pk_bf16_f32 v172, v112, v113
	v_cvt_pk_bf16_f32 v173, v114, v115
	global_store_dwordx4 v155, v[170:173], s[64:65]
	v_mul_f32_e32 v158, 0xbfb8aa3b, v201
	v_mul_f32_e32 v160, v201, v201
	v_pk_mul_f32 v[162:163], v[108:109], v[158:159] op_sel_hi:[1,0]
	v_pk_mul_f32 v[164:165], v[110:111], v[158:159] op_sel_hi:[1,0]
	v_pk_mul_f32 v[166:167], v[100:101], v[158:159] op_sel_hi:[1,0]
	v_pk_mul_f32 v[168:169], v[102:103], v[158:159] op_sel_hi:[1,0]
	v_exp_f32_e32 v162, v162
	v_exp_f32_e32 v163, v163
	v_pk_mul_f32 v[104:105], v[108:109], v[104:105]
	v_exp_f32_e32 v164, v164
	v_exp_f32_e32 v165, v165
	v_pk_mul_f32 v[106:107], v[110:111], v[106:107]
	v_exp_f32_e32 v166, v166
	v_exp_f32_e32 v167, v167
	v_pk_mul_f32 v[96:97], v[100:101], v[96:97]
	v_exp_f32_e32 v168, v168
	v_exp_f32_e32 v169, v169
	v_pk_mul_f32 v[98:99], v[102:103], v[98:99]
	v_pk_add_f32 v[162:163], v[162:163], v[198:199] op_sel_hi:[1,0]
	v_pk_add_f32 v[164:165], v[164:165], v[198:199] op_sel_hi:[1,0]
	v_pk_add_f32 v[166:167], v[166:167], v[198:199] op_sel_hi:[1,0]
	v_pk_add_f32 v[168:169], v[168:169], v[198:199] op_sel_hi:[1,0]
	v_rcp_f32_e32 v162, v162
	v_rcp_f32_e32 v163, v163
	v_rcp_f32_e32 v164, v164
	v_rcp_f32_e32 v165, v165
	v_rcp_f32_e32 v166, v166
	v_rcp_f32_e32 v167, v167
	v_rcp_f32_e32 v168, v168
	v_rcp_f32_e32 v169, v169
	v_pk_mul_f32 v[162:163], v[160:161], v[162:163] op_sel_hi:[0,1]
	v_pk_mul_f32 v[164:165], v[160:161], v[164:165] op_sel_hi:[0,1]
	v_pk_mul_f32 v[166:167], v[160:161], v[166:167] op_sel_hi:[0,1]
	v_pk_mul_f32 v[168:169], v[160:161], v[168:169] op_sel_hi:[0,1]
	v_pk_mul_f32 v[104:105], v[104:105], v[162:163]
	v_pk_mul_f32 v[106:107], v[106:107], v[164:165]
	v_pk_mul_f32 v[96:97], v[96:97], v[166:167]
	v_pk_mul_f32 v[98:99], v[98:99], v[168:169]
	v_cvt_pk_bf16_f32 v176, v104, v105
	v_cvt_pk_bf16_f32 v177, v106, v107
	v_cvt_pk_bf16_f32 v178, v96, v97
	v_cvt_pk_bf16_f32 v179, v98, v99
	v_add_u32_e32 v175, 0x16000, v155
	global_store_dwordx4 v175, v[176:179], s[64:65]
	v_mul_f32_e32 v158, 0xbfb8aa3b, v202
	v_mul_f32_e32 v160, v202, v202
	v_pk_mul_f32 v[162:163], v[92:93], v[158:159] op_sel_hi:[1,0]
	v_pk_mul_f32 v[164:165], v[94:95], v[158:159] op_sel_hi:[1,0]
	v_pk_mul_f32 v[166:167], v[84:85], v[158:159] op_sel_hi:[1,0]
	v_pk_mul_f32 v[168:169], v[86:87], v[158:159] op_sel_hi:[1,0]
	v_exp_f32_e32 v162, v162
	v_exp_f32_e32 v163, v163
	v_pk_mul_f32 v[88:89], v[92:93], v[88:89]
	v_exp_f32_e32 v164, v164
	v_exp_f32_e32 v165, v165
	v_pk_mul_f32 v[90:91], v[94:95], v[90:91]
	v_exp_f32_e32 v166, v166
	v_exp_f32_e32 v167, v167
	v_pk_mul_f32 v[80:81], v[84:85], v[80:81]
	v_exp_f32_e32 v168, v168
	v_exp_f32_e32 v169, v169
	v_pk_mul_f32 v[82:83], v[86:87], v[82:83]
	v_pk_add_f32 v[162:163], v[162:163], v[198:199] op_sel_hi:[1,0]
	v_pk_add_f32 v[164:165], v[164:165], v[198:199] op_sel_hi:[1,0]
	v_pk_add_f32 v[166:167], v[166:167], v[198:199] op_sel_hi:[1,0]
	v_pk_add_f32 v[168:169], v[168:169], v[198:199] op_sel_hi:[1,0]
	v_rcp_f32_e32 v162, v162
	v_rcp_f32_e32 v163, v163
	v_rcp_f32_e32 v164, v164
	v_rcp_f32_e32 v165, v165
	v_rcp_f32_e32 v166, v166
	v_rcp_f32_e32 v167, v167
	v_rcp_f32_e32 v168, v168
	v_rcp_f32_e32 v169, v169
	v_pk_mul_f32 v[162:163], v[160:161], v[162:163] op_sel_hi:[0,1]
	v_pk_mul_f32 v[164:165], v[160:161], v[164:165] op_sel_hi:[0,1]
	v_pk_mul_f32 v[166:167], v[160:161], v[166:167] op_sel_hi:[0,1]
	v_pk_mul_f32 v[168:169], v[160:161], v[168:169] op_sel_hi:[0,1]
; __device__ __forceinline__ unsigned cvt_pk_bf16(float lo, float hi) { unsigned r; asm volatile("v_cvt_pk_bf16_f32 %0, %1, %2" : "=v"(r) : "v"(lo), "v"(hi)); return r; }
;     __device__ __forceinline__ void operator()(Acc& acc, const Unit& u, int wr, int wc, int fr, int fq) const {
;         const int row0 = u.pm * BM + wr * 64 + fr, col0 = u.pn * 128 + wc * 32 + 8 * fq;
; #pragma unroll
;         for (int ai = 0; ai < 2; ++ai)
; #pragma unroll
;             for (int m = 0; m < 4; ++m) {
;                 const int row = row0 + ai * HALF + m * 16;
;                 const float r = rs[u.idx * BM + wr * 64 + fr + ai * HALF + m * 16];
;                 const float c1 = -r * 1.4426950408889634f, r2 = r * r;
;                 f32x4 o[2];
; #pragma unroll
;                 for (int n = 0; n < 2; ++n) {
;                     const f32x4 g = acc[ai][0][m][n], up = acc[ai][1][m][n];
;                     const f32x4 t = g * c1; f32x4 e;
; #pragma unroll
;                     for (int i = 0; i < 4; ++i) e[i] = __builtin_amdgcn_exp2f(t[i]);
;                     const f32x4 d = e + 1.0f; f32x4 q;
; #pragma unroll
;                     for (int i = 0; i < 4; ++i) q[i] = __builtin_amdgcn_rcpf(d[i]);
;                     o[n] = (g * up) * (q * r2);
;                 }
;                 u32x4 w; w.x = cvt_pk_bf16(o[0][0], o[0][1]); w.y = cvt_pk_bf16(o[0][2], o[0][3]); w.z = cvt_pk_bf16(o[1][0], o[1][1]); w.w = cvt_pk_bf16(o[1][2], o[1][3]);
;                 *(u32x4*)(O + (size_t)row * DFF + col0) = w;
;             }
	v_pk_mul_f32 v[88:89], v[88:89], v[162:163]
	v_pk_mul_f32 v[90:91], v[90:91], v[164:165]
	v_pk_mul_f32 v[80:81], v[80:81], v[166:167]
	v_pk_mul_f32 v[82:83], v[82:83], v[168:169]
	v_cvt_pk_bf16_f32 v170, v88, v89
	v_cvt_pk_bf16_f32 v171, v90, v91
	v_cvt_pk_bf16_f32 v172, v80, v81
	v_cvt_pk_bf16_f32 v173, v82, v83
	v_add_u32_e32 v174, 0x2c000, v155
	global_store_dwordx4 v174, v[170:173], s[64:65]
	v_mul_f32_e32 v158, 0xbfb8aa3b, v203
	v_mul_f32_e32 v160, v203, v203
	v_pk_mul_f32 v[162:163], v[76:77], v[158:159] op_sel_hi:[1,0]
	v_pk_mul_f32 v[164:165], v[78:79], v[158:159] op_sel_hi:[1,0]
	v_pk_mul_f32 v[166:167], v[68:69], v[158:159] op_sel_hi:[1,0]
	v_pk_mul_f32 v[168:169], v[70:71], v[158:159] op_sel_hi:[1,0]
	v_exp_f32_e32 v162, v162
	v_exp_f32_e32 v163, v163
	v_pk_mul_f32 v[72:73], v[76:77], v[72:73]
	v_exp_f32_e32 v164, v164
	v_exp_f32_e32 v165, v165
	v_pk_mul_f32 v[74:75], v[78:79], v[74:75]
	v_exp_f32_e32 v166, v166
	v_exp_f32_e32 v167, v167
	v_pk_mul_f32 v[64:65], v[68:69], v[64:65]
	v_exp_f32_e32 v168, v168
	v_exp_f32_e32 v169, v169
	v_pk_mul_f32 v[66:67], v[70:71], v[66:67]
	v_pk_add_f32 v[162:163], v[162:163], v[198:199] op_sel_hi:[1,0]
	v_pk_add_f32 v[164:165], v[164:165], v[198:199] op_sel_hi:[1,0]
	v_pk_add_f32 v[166:167], v[166:167], v[198:199] op_sel_hi:[1,0]
	v_pk_add_f32 v[168:169], v[168:169], v[198:199] op_sel_hi:[1,0]
	v_rcp_f32_e32 v162, v162
	v_rcp_f32_e32 v163, v163
	v_rcp_f32_e32 v164, v164
	v_rcp_f32_e32 v165, v165
	v_rcp_f32_e32 v166, v166
	v_rcp_f32_e32 v167, v167
	v_rcp_f32_e32 v168, v168
	v_rcp_f32_e32 v169, v169
	v_pk_mul_f32 v[162:163], v[160:161], v[162:163] op_sel_hi:[0,1]
	v_pk_mul_f32 v[164:165], v[160:161], v[164:165] op_sel_hi:[0,1]
	v_pk_mul_f32 v[166:167], v[160:161], v[166:167] op_sel_hi:[0,1]
	v_pk_mul_f32 v[168:169], v[160:161], v[168:169] op_sel_hi:[0,1]
	v_pk_mul_f32 v[72:73], v[72:73], v[162:163]
	v_pk_mul_f32 v[74:75], v[74:75], v[164:165]
	v_pk_mul_f32 v[64:65], v[64:65], v[166:167]
	v_pk_mul_f32 v[66:67], v[66:67], v[168:169]
	v_cvt_pk_bf16_f32 v176, v72, v73
	v_cvt_pk_bf16_f32 v177, v74, v75
	v_cvt_pk_bf16_f32 v178, v64, v65
	v_cvt_pk_bf16_f32 v179, v66, v67
	v_add_u32_e32 v175, 0x42000, v155
	global_store_dwordx4 v175, v[176:179], s[64:65]
	v_mul_f32_e32 v158, 0xbfb8aa3b, v204
	v_mul_f32_e32 v160, v204, v204
	v_pk_mul_f32 v[162:163], v[60:61], v[158:159] op_sel_hi:[1,0]
	v_pk_mul_f32 v[164:165], v[62:63], v[158:159] op_sel_hi:[1,0]
	v_pk_mul_f32 v[166:167], v[52:53], v[158:159] op_sel_hi:[1,0]
	v_pk_mul_f32 v[168:169], v[54:55], v[158:159] op_sel_hi:[1,0]
	v_exp_f32_e32 v162, v162
	v_exp_f32_e32 v163, v163
	v_pk_mul_f32 v[56:57], v[60:61], v[56:57]
	v_exp_f32_e32 v164, v164
	v_exp_f32_e32 v165, v165
	v_pk_mul_f32 v[58:59], v[62:63], v[58:59]
	v_exp_f32_e32 v166, v166
	v_exp_f32_e32 v167, v167
	v_pk_mul_f32 v[48:49], v[52:53], v[48:49]
	v_exp_f32_e32 v168, v168
	v_exp_f32_e32 v169, v169
	v_pk_mul_f32 v[50:51], v[54:55], v[50:51]
	v_pk_add_f32 v[162:163], v[162:163], v[198:199] op_sel_hi:[1,0]
	v_pk_add_f32 v[164:165], v[164:165], v[198:199] op_sel_hi:[1,0]
	v_pk_add_f32 v[166:167], v[166:167], v[198:199] op_sel_hi:[1,0]
	v_pk_add_f32 v[168:169], v[168:169], v[198:199] op_sel_hi:[1,0]
	v_rcp_f32_e32 v162, v162
	v_rcp_f32_e32 v163, v163
	v_rcp_f32_e32 v164, v164
	v_rcp_f32_e32 v165, v165
	v_rcp_f32_e32 v166, v166
	v_rcp_f32_e32 v167, v167
	v_rcp_f32_e32 v168, v168
	v_rcp_f32_e32 v169, v169
	v_pk_mul_f32 v[162:163], v[160:161], v[162:163] op_sel_hi:[0,1]
	v_pk_mul_f32 v[164:165], v[160:161], v[164:165] op_sel_hi:[0,1]
	v_pk_mul_f32 v[166:167], v[160:161], v[166:167] op_sel_hi:[0,1]
	v_pk_mul_f32 v[168:169], v[160:161], v[168:169] op_sel_hi:[0,1]
	v_pk_mul_f32 v[56:57], v[56:57], v[162:163]
	v_pk_mul_f32 v[58:59], v[58:59], v[164:165]
	v_pk_mul_f32 v[48:49], v[48:49], v[166:167]
	v_pk_mul_f32 v[50:51], v[50:51], v[168:169]
	v_cvt_pk_bf16_f32 v170, v56, v57
	v_cvt_pk_bf16_f32 v171, v58, v59
	v_cvt_pk_bf16_f32 v172, v48, v49
	v_cvt_pk_bf16_f32 v173, v50, v51
	v_add_u32_e32 v174, 0xb0000, v155
	global_store_dwordx4 v174, v[170:173], s[64:65]
	v_mul_f32_e32 v158, 0xbfb8aa3b, v205
	v_mul_f32_e32 v160, v205, v205
	v_pk_mul_f32 v[162:163], v[44:45], v[158:159] op_sel_hi:[1,0]
	v_pk_mul_f32 v[164:165], v[46:47], v[158:159] op_sel_hi:[1,0]
	v_pk_mul_f32 v[166:167], v[36:37], v[158:159] op_sel_hi:[1,0]
	v_pk_mul_f32 v[168:169], v[38:39], v[158:159] op_sel_hi:[1,0]
	v_exp_f32_e32 v162, v162
	v_exp_f32_e32 v163, v163
	v_pk_mul_f32 v[40:41], v[44:45], v[40:41]
	v_exp_f32_e32 v164, v164
	v_exp_f32_e32 v165, v165
	v_pk_mul_f32 v[42:43], v[46:47], v[42:43]
	v_exp_f32_e32 v166, v166
	v_exp_f32_e32 v167, v167
	v_pk_mul_f32 v[32:33], v[36:37], v[32:33]
	v_exp_f32_e32 v168, v168
	v_exp_f32_e32 v169, v169
	v_pk_mul_f32 v[34:35], v[38:39], v[34:35]
	v_pk_add_f32 v[162:163], v[162:163], v[198:199] op_sel_hi:[1,0]
; __device__ __forceinline__ unsigned cvt_pk_bf16(float lo, float hi) { unsigned r; asm volatile("v_cvt_pk_bf16_f32 %0, %1, %2" : "=v"(r) : "v"(lo), "v"(hi)); return r; }
;     __device__ __forceinline__ void operator()(Acc& acc, const Unit& u, int wr, int wc, int fr, int fq) const {
;         const int row0 = u.pm * BM + wr * 64 + fr, col0 = u.pn * 128 + wc * 32 + 8 * fq;
; #pragma unroll
;         for (int ai = 0; ai < 2; ++ai)
; #pragma unroll
;             for (int m = 0; m < 4; ++m) {
;                 const int row = row0 + ai * HALF + m * 16;
;                 const float r = rs[u.idx * BM + wr * 64 + fr + ai * HALF + m * 16];
;                 const float c1 = -r * 1.4426950408889634f, r2 = r * r;
;                 f32x4 o[2];
; #pragma unroll
;                 for (int n = 0; n < 2; ++n) {
;                     const f32x4 g = acc[ai][0][m][n], up = acc[ai][1][m][n];
;                     const f32x4 t = g * c1; f32x4 e;
; #pragma unroll
;                     for (int i = 0; i < 4; ++i) e[i] = __builtin_amdgcn_exp2f(t[i]);
;                     const f32x4 d = e + 1.0f; f32x4 q;
; #pragma unroll
;                     for (int i = 0; i < 4; ++i) q[i] = __builtin_amdgcn_rcpf(d[i]);
;                     o[n] = (g * up) * (q * r2);
;                 }
;                 u32x4 w; w.x = cvt_pk_bf16(o[0][0], o[0][1]); w.y = cvt_pk_bf16(o[0][2], o[0][3]); w.z = cvt_pk_bf16(o[1][0], o[1][1]); w.w = cvt_pk_bf16(o[1][2], o[1][3]);
;                 *(u32x4*)(O + (size_t)row * DFF + col0) = w;
;             }
	v_pk_add_f32 v[164:165], v[164:165], v[198:199] op_sel_hi:[1,0]
	v_pk_add_f32 v[166:167], v[166:167], v[198:199] op_sel_hi:[1,0]
	v_pk_add_f32 v[168:169], v[168:169], v[198:199] op_sel_hi:[1,0]
	v_rcp_f32_e32 v162, v162
	v_rcp_f32_e32 v163, v163
	v_rcp_f32_e32 v164, v164
	v_rcp_f32_e32 v165, v165
	v_rcp_f32_e32 v166, v166
	v_rcp_f32_e32 v167, v167
	v_rcp_f32_e32 v168, v168
	v_rcp_f32_e32 v169, v169
	v_pk_mul_f32 v[162:163], v[160:161], v[162:163] op_sel_hi:[0,1]
	v_pk_mul_f32 v[164:165], v[160:161], v[164:165] op_sel_hi:[0,1]
	v_pk_mul_f32 v[166:167], v[160:161], v[166:167] op_sel_hi:[0,1]
	v_pk_mul_f32 v[168:169], v[160:161], v[168:169] op_sel_hi:[0,1]
	v_pk_mul_f32 v[40:41], v[40:41], v[162:163]
	v_pk_mul_f32 v[42:43], v[42:43], v[164:165]
	v_pk_mul_f32 v[32:33], v[32:33], v[166:167]
	v_pk_mul_f32 v[34:35], v[34:35], v[168:169]
	v_cvt_pk_bf16_f32 v176, v40, v41
	v_cvt_pk_bf16_f32 v177, v42, v43
	v_cvt_pk_bf16_f32 v178, v32, v33
	v_cvt_pk_bf16_f32 v179, v34, v35
	v_add_u32_e32 v175, 0xc6000, v155
	global_store_dwordx4 v175, v[176:179], s[64:65]
	v_mul_f32_e32 v158, 0xbfb8aa3b, v206
	v_mul_f32_e32 v160, v206, v206
	v_pk_mul_f32 v[162:163], v[28:29], v[158:159] op_sel_hi:[1,0]
	v_pk_mul_f32 v[164:165], v[30:31], v[158:159] op_sel_hi:[1,0]
	v_pk_mul_f32 v[166:167], v[20:21], v[158:159] op_sel_hi:[1,0]
	v_pk_mul_f32 v[168:169], v[22:23], v[158:159] op_sel_hi:[1,0]
	v_exp_f32_e32 v162, v162
	v_exp_f32_e32 v163, v163
	v_pk_mul_f32 v[24:25], v[28:29], v[24:25]
	v_exp_f32_e32 v164, v164
	v_exp_f32_e32 v165, v165
	v_pk_mul_f32 v[26:27], v[30:31], v[26:27]
	v_exp_f32_e32 v166, v166
	v_exp_f32_e32 v167, v167
	v_pk_mul_f32 v[16:17], v[20:21], v[16:17]
	v_exp_f32_e32 v168, v168
	v_exp_f32_e32 v169, v169
	v_pk_mul_f32 v[18:19], v[22:23], v[18:19]
	v_pk_add_f32 v[162:163], v[162:163], v[198:199] op_sel_hi:[1,0]
	v_pk_add_f32 v[164:165], v[164:165], v[198:199] op_sel_hi:[1,0]
	v_pk_add_f32 v[166:167], v[166:167], v[198:199] op_sel_hi:[1,0]
	v_pk_add_f32 v[168:169], v[168:169], v[198:199] op_sel_hi:[1,0]
	v_rcp_f32_e32 v162, v162
	v_rcp_f32_e32 v163, v163
	v_rcp_f32_e32 v164, v164
	v_rcp_f32_e32 v165, v165
	v_rcp_f32_e32 v166, v166
	v_rcp_f32_e32 v167, v167
	v_rcp_f32_e32 v168, v168
	v_rcp_f32_e32 v169, v169
	v_pk_mul_f32 v[162:163], v[160:161], v[162:163] op_sel_hi:[0,1]
	v_pk_mul_f32 v[164:165], v[160:161], v[164:165] op_sel_hi:[0,1]
	v_pk_mul_f32 v[166:167], v[160:161], v[166:167] op_sel_hi:[0,1]
	v_pk_mul_f32 v[168:169], v[160:161], v[168:169] op_sel_hi:[0,1]
	v_pk_mul_f32 v[24:25], v[24:25], v[162:163]
	v_pk_mul_f32 v[26:27], v[26:27], v[164:165]
	v_pk_mul_f32 v[16:17], v[16:17], v[166:167]
	v_pk_mul_f32 v[18:19], v[18:19], v[168:169]
	v_cvt_pk_bf16_f32 v170, v24, v25
	v_cvt_pk_bf16_f32 v171, v26, v27
	v_cvt_pk_bf16_f32 v172, v16, v17
	v_cvt_pk_bf16_f32 v173, v18, v19
	v_add_u32_e32 v174, 0xdc000, v155
	global_store_dwordx4 v174, v[170:173], s[64:65]
	v_mul_f32_e32 v158, 0xbfb8aa3b, v207
	v_mul_f32_e32 v160, v207, v207
	v_pk_mul_f32 v[162:163], v[12:13], v[158:159] op_sel_hi:[1,0]
	v_pk_mul_f32 v[164:165], v[14:15], v[158:159] op_sel_hi:[1,0]
	v_pk_mul_f32 v[166:167], v[4:5], v[158:159] op_sel_hi:[1,0]
	v_pk_mul_f32 v[168:169], v[6:7], v[158:159] op_sel_hi:[1,0]
	v_exp_f32_e32 v162, v162
	v_exp_f32_e32 v163, v163
	v_pk_mul_f32 v[8:9], v[12:13], v[8:9]
	v_exp_f32_e32 v164, v164
	v_exp_f32_e32 v165, v165
	v_pk_mul_f32 v[10:11], v[14:15], v[10:11]
	v_exp_f32_e32 v166, v166
	v_exp_f32_e32 v167, v167
	v_pk_mul_f32 v[0:1], v[4:5], v[0:1]
	v_exp_f32_e32 v168, v168
	v_exp_f32_e32 v169, v169
	v_pk_mul_f32 v[2:3], v[6:7], v[2:3]
	v_pk_add_f32 v[162:163], v[162:163], v[198:199] op_sel_hi:[1,0]
	v_pk_add_f32 v[164:165], v[164:165], v[198:199] op_sel_hi:[1,0]
	v_pk_add_f32 v[166:167], v[166:167], v[198:199] op_sel_hi:[1,0]
	v_pk_add_f32 v[168:169], v[168:169], v[198:199] op_sel_hi:[1,0]
	v_rcp_f32_e32 v162, v162
	v_rcp_f32_e32 v163, v163
	v_rcp_f32_e32 v164, v164
	v_rcp_f32_e32 v165, v165
	v_rcp_f32_e32 v166, v166
	v_rcp_f32_e32 v167, v167
	v_rcp_f32_e32 v168, v168
	v_rcp_f32_e32 v169, v169
	v_pk_mul_f32 v[162:163], v[160:161], v[162:163] op_sel_hi:[0,1]
	v_pk_mul_f32 v[164:165], v[160:161], v[164:165] op_sel_hi:[0,1]
	v_pk_mul_f32 v[166:167], v[160:161], v[166:167] op_sel_hi:[0,1]
	v_pk_mul_f32 v[168:169], v[160:161], v[168:169] op_sel_hi:[0,1]
	v_pk_mul_f32 v[8:9], v[8:9], v[162:163]
	v_pk_mul_f32 v[10:11], v[10:11], v[164:165]
	v_pk_mul_f32 v[0:1], v[0:1], v[166:167]
	v_pk_mul_f32 v[2:3], v[2:3], v[168:169]
	v_cvt_pk_bf16_f32 v176, v8, v9
	v_cvt_pk_bf16_f32 v177, v10, v11
	v_cvt_pk_bf16_f32 v178, v0, v1
	v_cvt_pk_bf16_f32 v179, v2, v3
	v_add_u32_e32 v175, 0xf2000, v155
	global_store_dwordx4 v175, v[176:179], s[64:65]
	s_andn2_b64 vcc, exec, s[2:3]
	s_mov_b64 s[2:3], -1
	s_mov_b32 s101, 1
	s_cbranch_vccnz .LBB0_1609
	s_andn2_b64 vcc, exec, s[4:5]
	s_cbranch_vccnz .LBB0_1608
	s_barrier
	s_branch .LBB0_1608
